# mix rebalance variant: overloaded WGs take 2 window-attn + 2 ctx items, 256 WGs take 5 window-attn items, 128 WGs take 4 window-attn + 2 ctx items
# baseline (speedup 1.0000x reference)
.LBB0_645:
	s_add_i32 s54, s62, s85
	s_cmpk_lg_u32 s33, 0x200
	s_cbranch_scc1 .Lmixbal_done
	s_cmpk_lt_u32 s85, 0x80
	s_cbranch_scc0 .Lmixbal_hi
	s_cmpk_lg_u32 s62, 0xe00
	s_cbranch_scc1 .Lmixbal_lo2
	s_add_i32 s54, s85, 0x1480
	s_branch .Lmixbal_done
.Lmixbal_lo2:
	s_cmpk_lg_u32 s62, 0x1400
	s_cbranch_scc1 .Lmixbal_done
	s_movk_i32 s54, 0x1680
	s_branch .Lmixbal_done
.Lmixbal_hi:
	s_cmpk_lt_u32 s85, 0x180
	s_cbranch_scc0 .Lmixbal_b
	s_cmpk_lg_u32 s62, 0x1400
	s_cbranch_scc1 .Lmixbal_done
	s_sub_i32 s98, s85, 0x80
	s_add_i32 s54, s98, 0xe00
	s_cmpk_lt_u32 s98, 0x80
	s_cbranch_scc1 .Lmixbal_done
	s_add_i32 s54, s98, 0x1380
	s_branch .Lmixbal_done
.Lmixbal_b:
	s_cmpk_lg_u32 s62, 0x1600
	s_cbranch_scc1 .Lmixbal_done
	s_add_i32 s54, s85, 0x1380
